# P0 conversion loop: gain loads hoisted to the tile-load stage, counted vmcnt waits so the next tile's loads and previous stores stay in flight
# baseline (speedup 1.0000x reference)
; #define LAS __attribute__((address_space(3)))
; __device__ __forceinline__ void p0_load(const float* W, int N, int k0, int n0, int lane, f32x4 (&v)[16]) {
;     const int c = lane & 15, rq = lane >> 4;
;     int col = n0 + 4 * c; col = col < N - 4 ? col : N - 4;
;     const float* p = W + (size_t)(k0 + rq) * N + col;
; #pragma unroll
;     for (int j = 0; j < 16; ++j) v[j] = __builtin_nontemporal_load((const f32x4*)(p + (size_t)(4 * j) * N));
; }
; __device__ __forceinline__ void p0_finish(bf16* WT, const float* gain, int N, int k0, int n0, int ldw, int blk, int off, int lane, const f32x4 (&v)[16], LAS float* scr) {
;     const int c = lane & 15, rq = lane >> 4, c8 = lane & 7;
;     f32x4 g0 = {1.f, 1.f, 1.f, 1.f}, g1 = g0;
;     if (gain) { g0 = *(const f32x4*)(gain + k0 + 8 * c8); g1 = *(const f32x4*)(gain + k0 + 8 * c8 + 4); }
.LBB0_20:
	v_ashrrev_i32_e32 v141, 4, v140
	v_lshlrev_b32_e32 v0, 2, v140
	v_and_b32_e32 v143, 60, v0
	s_load_dwordx2 s[20:21], s[42:43], 0x0
	v_add_u32_e32 v0, s30, v141
	v_ashrrev_i32_e32 v3, 31, v0
	v_mad_u64_u32 v[0:1], s[42:43], v0, s24, 0
	v_mov_b32_e32 v2, v1
	v_mad_u64_u32 v[2:3], s[42:43], v3, s24, v[2:3]
	v_mov_b32_e32 v1, v2
	s_waitcnt lgkmcnt(0)
	v_lshl_add_u64 v[0:1], v[0:1], 2, s[20:21]
	v_add_u32_e32 v2, s17, v143
	s_add_i32 s20, s24, -4
	v_min_i32_e32 v2, s20, v2
	v_ashrrev_i32_e32 v3, 31, v2
	v_lshl_add_u64 v[60:61], v[2:3], 2, v[0:1]
	s_mul_i32 s38, s24, 60
	v_lshl_add_u64 v[62:63], s[38:39], 2, v[60:61]
	s_mul_i32 s38, s24, 56
	v_lshl_add_u64 v[0:1], s[38:39], 2, v[60:61]
	s_mul_i32 s38, s24, 52
	v_lshl_add_u64 v[2:3], s[38:39], 2, v[60:61]
	s_mul_i32 s38, s24, 48
	v_lshl_add_u64 v[8:9], s[38:39], 2, v[60:61]
	s_mul_i32 s38, s24, 44
	v_lshl_add_u64 v[10:11], s[38:39], 2, v[60:61]
	s_mul_i32 s38, s24, 40
	v_lshl_add_u64 v[24:25], s[38:39], 2, v[60:61]
	s_mul_i32 s38, s24, 36
	v_lshl_add_u64 v[26:27], s[38:39], 2, v[60:61]
	s_lshl_b32 s38, s24, 5
	global_load_dwordx4 v[12:15], v[0:1], off nt
	s_nop 0
	global_load_dwordx4 v[0:3], v[2:3], off nt
	s_nop 0
	global_load_dwordx4 v[16:19], v[8:9], off nt
	global_load_dwordx4 v[4:7], v[10:11], off nt
	global_load_dwordx4 v[20:23], v[24:25], off nt
	s_nop 0
	global_load_dwordx4 v[8:11], v[26:27], off nt
	v_lshl_add_u64 v[24:25], s[38:39], 2, v[60:61]
	s_mul_i32 s38, s24, 28
	v_lshl_add_u64 v[26:27], s[38:39], 2, v[60:61]
	s_mul_i32 s38, s24, 24
	v_lshl_add_u64 v[28:29], s[38:39], 2, v[60:61]
	s_mul_i32 s38, s24, 20
	v_lshl_add_u64 v[30:31], s[38:39], 2, v[60:61]
	s_lshl_b32 s38, s24, 4
	v_lshl_add_u64 v[36:37], s[38:39], 2, v[60:61]
	s_mul_i32 s38, s24, 12
	v_lshl_add_u64 v[38:39], s[38:39], 2, v[60:61]
	s_lshl_b32 s38, s24, 3
	global_load_dwordx4 v[56:59], v[24:25], off nt
	global_load_dwordx4 v[48:51], v[26:27], off nt
	global_load_dwordx4 v[52:55], v[28:29], off nt
	global_load_dwordx4 v[40:43], v[30:31], off nt
	global_load_dwordx4 v[44:47], v[36:37], off nt
	global_load_dwordx4 v[32:35], v[38:39], off nt
	v_lshl_add_u64 v[64:65], s[38:39], 2, v[60:61]
	s_lshl_b32 s38, s24, 2
	v_lshl_add_u64 v[66:67], s[38:39], 2, v[60:61]
	global_load_dwordx4 v[36:39], v[64:65], off nt
	global_load_dwordx4 v[24:27], v[66:67], off nt
	global_load_dwordx4 v[68:71], v[62:63], off nt
	global_load_dwordx4 v[28:31], v[60:61], off nt
	s_add_u32 s42, s0, 48
	s_load_dwordx2 s[44:45], s[0:1], 0x8
	s_load_dwordx2 s[46:47], s[0:1], 0x28
	s_addc_u32 s43, s1, 0
	s_add_u32 s48, s0, 32
	v_and_b32_e32 v60, 7, v140
	s_movk_i32 s20, 0x104
	v_ashrrev_i32_e32 v148, 3, v140
	s_addc_u32 s49, s1, 0
	v_lshlrev_b32_e32 v142, 3, v60
	v_lshl_add_u32 v61, v143, 2, s19
	v_mul_lo_u32 v62, v141, s20
	v_mul_u32_u24_e32 v60, 0x820, v60
	v_lshlrev_b32_e32 v63, 2, v148
	s_lshl_b32 s20, s75, 9
	v_mov_b32_e32 v145, 0
	v_add3_u32 v149, s19, v60, v63
	v_add_u32_e32 v150, 8, v148
	v_add_u32_e32 v151, 16, v148
	v_add_u32_e32 v152, 24, v148
	v_add_u32_e32 v153, 32, v148
	v_add_u32_e32 v154, 40, v148
	v_add_u32_e32 v155, 48, v148
	v_add_u32_e32 v156, v61, v62
	v_add_u32_e32 v157, 56, v148
	s_lshl_b32 s63, s33, 4
	s_lshl_b32 s64, s33, 10
	s_add_i32 s65, s20, s9
	s_lshl_b32 s66, s33, 9
	s_mov_b64 s[50:51], 0
	v_lshlrev_b32_e32 v144, 1, v142
	s_mov_b64 s[54:55], 0
	s_mov_b32 s69, 0
	s_mov_b32 s52, s39
	s_mov_b32 s68, 0
	s_mov_b32 s70, 0
	s_mov_b32 s20, 0
	s_mov_b32 s71, 0
	s_mov_b32 s67, s16
	s_ashr_i32 s31, s30, 31
	s_cmp_eq_u64 s[4:5], 0
	s_cbranch_scc1 .Lp0g_pro_nog
	s_lshl_b64 s[98:99], s[30:31], 2
	s_add_u32 s98, s4, s98
	s_addc_u32 s99, s5, s99
	v_lshlrev_b32_e32 v132, 2, v142
	global_load_dwordx4 v[128:131], v132, s[98:99] offset:16
	s_nop 0
	global_load_dwordx4 v[132:135], v132, s[98:99]
	s_branch .Lp0g_pro_done
.Lp0g_pro_nog:
	v_mov_b32_e32 v128, 1.0
	v_mov_b32_e32 v129, 1.0
	v_mov_b32_e32 v130, 1.0
	v_mov_b32_e32 v131, 1.0
	v_mov_b32_e32 v132, 1.0
	v_mov_b32_e32 v133, 1.0
	v_mov_b32_e32 v134, 1.0
	v_mov_b32_e32 v135, 1.0
	s_mov_b64 exec, 0
	global_load_dword v227, v[226:227], off
	global_load_dword v227, v[226:227], off
	s_mov_b64 exec, -1
.Lp0g_pro_done:
	s_mov_b64 exec, 0
	global_store_dword v[226:227], v227, off
	global_store_dword v[226:227], v227, off
	global_store_dword v[226:227], v227, off
	global_store_dword v[226:227], v227, off
	global_store_dword v[226:227], v227, off
	global_store_dword v[226:227], v227, off
	global_store_dword v[226:227], v227, off
	global_store_dword v[226:227], v227, off
	s_mov_b64 exec, -1
	s_branch .LBB0_23

; #define LAS __attribute__((address_space(3)))
; __device__ __forceinline__ unsigned pk2(float lo, float hi) { return pg8::cvt_pk_bf16(lo, hi); }
; __device__ __forceinline__ void p0_finish(bf16* WT, const float* gain, int N, int k0, int n0, int ldw, int blk, int off, int lane, const f32x4 (&v)[16], LAS float* scr) {
;     const int c = lane & 15, rq = lane >> 4, c8 = lane & 7;
;     f32x4 g0 = {1.f, 1.f, 1.f, 1.f}, g1 = g0;
;     if (gain) { g0 = *(const f32x4*)(gain + k0 + 8 * c8); g1 = *(const f32x4*)(gain + k0 + 8 * c8 + 4); }
; #pragma unroll
;     for (int j = 0; j < 16; ++j) { LAS float* s = scr + (4 * j + rq) * 65 + 4 * c; s[0] = v[j][0]; s[1] = v[j][1]; s[2] = v[j][2]; s[3] = v[j][3]; }
;     asm volatile("s_waitcnt lgkmcnt(0)" ::: "memory");
; #pragma unroll
;     for (int jj = 0; jj < 8; ++jj) { const int n = (lane >> 3) + 8 * jj; const LAS float* s = scr + (8 * c8) * 65 + n;
;         u32x4 o; o.x = pk2(s[0 * 65] * g0[0], s[1 * 65] * g0[1]); o.y = pk2(s[2 * 65] * g0[2], s[3 * 65] * g0[3]); o.z = pk2(s[4 * 65] * g1[0], s[5 * 65] * g1[1]); o.w = pk2(s[6 * 65] * g1[2], s[7 * 65] * g1[3]);
;         const int ng = n0 + n;
;         if (ng < N) { const int row = (ng >> 7) * blk + (ng & 127) + off; __builtin_nontemporal_store(o, (u32x4*)(WT + (size_t)row * ldw + k0 + 8 * c8)); } }
.LBB0_34:
	s_ashr_i32 s53, s52, 31
	s_cmp_eq_u64 s[50:51], 0
	s_cbranch_scc1 .LBB0_36
	s_lshl_b64 s[58:59], s[52:53], 2
	s_add_u32 s58, s50, s58
	s_addc_u32 s59, s51, s59
	v_lshlrev_b32_e32 v232, 2, v142
	global_load_dwordx4 v[228:231], v232, s[58:59] offset:16
	s_nop 0
	global_load_dwordx4 v[232:235], v232, s[58:59]
	s_branch .LBB0_37
.LBB0_36:
	v_mov_b32_e32 v228, 1.0
	v_mov_b32_e32 v229, 1.0
	v_mov_b32_e32 v230, 1.0
	v_mov_b32_e32 v231, 1.0
	v_mov_b32_e32 v232, 1.0
	v_mov_b32_e32 v233, 1.0
	v_mov_b32_e32 v234, 1.0
	v_mov_b32_e32 v235, 1.0
	s_mov_b64 exec, 0
	global_load_dword v227, v[226:227], off
	global_load_dword v227, v[226:227], off
	s_mov_b64 exec, -1
.LBB0_37:
	v_add_u32_e32 v159, 0x410, v156
	v_add_u32_e32 v160, 0x418, v156
	v_add_u32_e32 v161, 0x820, v156
	v_add_u32_e32 v162, 0x828, v156
	v_add_u32_e32 v163, 0xc30, v156
	v_add_u32_e32 v164, 0xc38, v156
	v_add_u32_e32 v165, 0x1040, v156
	v_add_u32_e32 v166, 0x1048, v156
	v_add_u32_e32 v167, 0x1450, v156
	v_add_u32_e32 v168, 0x1458, v156
	v_add_u32_e32 v169, 0x1860, v156
	v_add_u32_e32 v170, 0x1868, v156
	v_add_u32_e32 v171, 0x1c70, v156
	v_add_u32_e32 v172, 0x1c78, v156
	v_add_u32_e32 v173, 0x2080, v156
	v_add_u32_e32 v174, 0x2088, v156
	v_add_u32_e32 v175, 0x2490, v156
	v_add_u32_e32 v176, 0x2498, v156
	v_add_u32_e32 v177, 0x28a0, v156
	v_add_u32_e32 v178, 0x28a8, v156
	v_add_u32_e32 v179, 0x2cb0, v156
	v_add_u32_e32 v180, 0x2cb8, v156
	v_add_u32_e32 v181, 0x30c0, v156
	v_add_u32_e32 v182, 0x30c8, v156
	v_add_u32_e32 v183, 0x34d0, v156
	v_add_u32_e32 v184, 0x34d8, v156
	v_add_u32_e32 v185, 0x38e0, v156
	v_add_u32_e32 v186, 0x38e8, v156
	v_add_u32_e32 v187, 0x3cf0, v156
	v_add_u32_e32 v188, 0x3cf8, v156
	s_ashr_i32 s31, s30, 31
	s_cmp_lg_u64 s[56:57], 0
	s_cbranch_scc0 .Lp0w_a0
	s_waitcnt vmcnt(26)
	s_branch .Lp0w_a1
.Lp0w_a0:
	s_waitcnt vmcnt(8)
.Lp0w_a1:
	ds_write2_b32 v156, v28, v29 offset1:1
	ds_write2_b32 v156, v30, v31 offset0:2 offset1:3
	ds_write2_b32 v159, v24, v25 offset1:1
	ds_write2_b32 v160, v26, v27 offset1:1
	ds_write2_b32 v161, v36, v37 offset1:1
	ds_write2_b32 v162, v38, v39 offset1:1
	ds_write2_b32 v163, v32, v33 offset1:1
	ds_write2_b32 v164, v34, v35 offset1:1
	ds_write2_b32 v165, v44, v45 offset1:1
	ds_write2_b32 v166, v46, v47 offset1:1
	ds_write2_b32 v167, v40, v41 offset1:1
	ds_write2_b32 v168, v42, v43 offset1:1
	ds_write2_b32 v169, v52, v53 offset1:1
	ds_write2_b32 v170, v54, v55 offset1:1
	ds_write2_b32 v171, v48, v49 offset1:1
	ds_write2_b32 v172, v50, v51 offset1:1
	ds_write2_b32 v173, v56, v57 offset1:1
	ds_write2_b32 v174, v58, v59 offset1:1
	ds_write2_b32 v175, v8, v9 offset1:1
	ds_write2_b32 v176, v10, v11 offset1:1
	ds_write2_b32 v177, v20, v21 offset1:1
	ds_write2_b32 v178, v22, v23 offset1:1
	ds_write2_b32 v179, v4, v5 offset1:1
	ds_write2_b32 v180, v6, v7 offset1:1
	ds_write2_b32 v181, v16, v17 offset1:1
	ds_write2_b32 v182, v18, v19 offset1:1
	ds_write2_b32 v183, v0, v1 offset1:1
	ds_write2_b32 v184, v2, v3 offset1:1
	ds_write2_b32 v185, v12, v13 offset1:1
	ds_write2_b32 v186, v14, v15 offset1:1
	ds_write2_b32 v187, v68, v69 offset1:1
	ds_write2_b32 v188, v70, v71 offset1:1
	s_waitcnt lgkmcnt(0)
	ds_read2_b32 v[136:137], v149 offset1:65
	v_add_u32_e32 v158, 0x400, v149
	s_lshl_b64 s[58:59], s[30:31], 1
	s_add_u32 s58, s40, s58
	s_addc_u32 s59, s41, s59
	s_waitcnt lgkmcnt(0)
	v_mul_f32_e32 v136, v132, v136
	v_mul_f32_e32 v137, v133, v137
	v_cvt_pk_bf16_f32 v136, v136, v137
	ds_read2_b32 v[138:139], v149 offset0:130 offset1:195
	v_lshl_add_u64 v[146:147], s[58:59], 0, v[144:145]
	s_waitcnt lgkmcnt(0)
	v_mul_f32_e32 v137, v134, v138
	v_mul_f32_e32 v138, v135, v139
	v_cvt_pk_bf16_f32 v137, v137, v138
	ds_read2_b32 v[138:139], v158 offset0:4 offset1:69
	s_waitcnt lgkmcnt(0)
	v_mul_f32_e32 v138, v128, v138
	v_mul_f32_e32 v139, v129, v139
	v_cvt_pk_bf16_f32 v138, v138, v139
	ds_read2_b32 v[190:191], v158 offset0:134 offset1:199
	s_waitcnt lgkmcnt(0)
	v_mul_f32_e32 v139, v130, v190
	v_mul_f32_e32 v189, v131, v191
	v_cvt_pk_bf16_f32 v139, v139, v189
	v_add_u32_e32 v189, s17, v148
	v_cmp_gt_i32_e32 vcc, s24, v189
	s_and_saveexec_b64 s[58:59], vcc
	v_ashrrev_i32_e32 v190, 7, v189
	v_mul_lo_u32 v190, v190, s29
	v_and_b32_e32 v189, 0x7f, v189
	v_add3_u32 v189, v189, s62, v190
	v_mad_u64_u32 v[190:191], s[60:61], v189, s25, 0
	v_ashrrev_i32_e32 v193, 31, v189
	v_mov_b32_e32 v192, v191
	v_mad_u64_u32 v[192:193], s[60:61], v193, s25, v[192:193]
	v_mov_b32_e32 v191, v192
	v_lshl_add_u64 v[190:191], v[190:191], 1, v[146:147]
	global_store_dwordx4 v[190:191], v[136:139], off nt
.LBB0_39:
	s_or_b64 exec, exec, s[58:59]
	ds_read2_b32 v[136:137], v149 offset0:8 offset1:73
	v_add_u32_e32 v189, s17, v150
	v_cmp_gt_i32_e32 vcc, s24, v189
	s_waitcnt lgkmcnt(0)
	v_mul_f32_e32 v136, v132, v136
	v_mul_f32_e32 v137, v133, v137
	v_cvt_pk_bf16_f32 v136, v136, v137
	ds_read2_b32 v[138:139], v149 offset0:138 offset1:203
	s_waitcnt lgkmcnt(0)
	v_mul_f32_e32 v137, v134, v138
	v_mul_f32_e32 v138, v135, v139
	v_cvt_pk_bf16_f32 v137, v137, v138
	ds_read2_b32 v[138:139], v158 offset0:12 offset1:77
	s_waitcnt lgkmcnt(0)
	v_mul_f32_e32 v138, v128, v138
	v_mul_f32_e32 v139, v129, v139
	v_cvt_pk_bf16_f32 v138, v138, v139
	ds_read2_b32 v[190:191], v158 offset0:142 offset1:207
	s_waitcnt lgkmcnt(0)
	v_mul_f32_e32 v139, v130, v190
	v_mul_f32_e32 v190, v131, v191
	v_cvt_pk_bf16_f32 v139, v139, v190
	s_and_saveexec_b64 s[58:59], vcc
	v_ashrrev_i32_e32 v190, 7, v189
	v_mul_lo_u32 v190, v190, s29
	v_and_b32_e32 v189, 0x7f, v189
	v_add3_u32 v189, v189, s62, v190
	v_mad_u64_u32 v[190:191], s[60:61], v189, s25, 0
	v_ashrrev_i32_e32 v193, 31, v189
	v_mov_b32_e32 v192, v191
	v_mad_u64_u32 v[192:193], s[60:61], v193, s25, v[192:193]
	v_mov_b32_e32 v191, v192
	v_lshl_add_u64 v[190:191], v[190:191], 1, v[146:147]
	global_store_dwordx4 v[190:191], v[136:139], off nt
; #define LAS __attribute__((address_space(3)))
; __device__ __forceinline__ unsigned pk2(float lo, float hi) { return pg8::cvt_pk_bf16(lo, hi); }
; __device__ __forceinline__ void p0_finish(bf16* WT, const float* gain, int N, int k0, int n0, int ldw, int blk, int off, int lane, const f32x4 (&v)[16], LAS float* scr) {
;     ...
;     for (int jj = 0; jj < 8; ++jj) { const int n = (lane >> 3) + 8 * jj; const LAS float* s = scr + (8 * c8) * 65 + n;
;         u32x4 o; o.x = pk2(s[0 * 65] * g0[0], s[1 * 65] * g0[1]); o.y = pk2(s[2 * 65] * g0[2], s[3 * 65] * g0[3]); o.z = pk2(s[4 * 65] * g1[0], s[5 * 65] * g1[1]); o.w = pk2(s[6 * 65] * g1[2], s[7 * 65] * g1[3]);
;         const int ng = n0 + n;
;         if (ng < N) { const int row = (ng >> 7) * blk + (ng & 127) + off; __builtin_nontemporal_store(o, (u32x4*)(WT + (size_t)row * ldw + k0 + 8 * c8)); } }
.LBB0_41:
	s_or_b64 exec, exec, s[58:59]
	ds_read2_b32 v[136:137], v149 offset0:16 offset1:81
	v_add_u32_e32 v189, s17, v151
	v_cmp_gt_i32_e32 vcc, s24, v189
	s_waitcnt lgkmcnt(0)
	v_mul_f32_e32 v136, v132, v136
	v_mul_f32_e32 v137, v133, v137
	v_cvt_pk_bf16_f32 v136, v136, v137
	ds_read2_b32 v[138:139], v149 offset0:146 offset1:211
	s_waitcnt lgkmcnt(0)
	v_mul_f32_e32 v137, v134, v138
	v_mul_f32_e32 v138, v135, v139
	v_cvt_pk_bf16_f32 v137, v137, v138
	ds_read2_b32 v[138:139], v158 offset0:20 offset1:85
	s_waitcnt lgkmcnt(0)
	v_mul_f32_e32 v138, v128, v138
	v_mul_f32_e32 v139, v129, v139
	v_cvt_pk_bf16_f32 v138, v138, v139
	ds_read2_b32 v[190:191], v158 offset0:150 offset1:215
	s_waitcnt lgkmcnt(0)
	v_mul_f32_e32 v139, v130, v190
	v_mul_f32_e32 v190, v131, v191
	v_cvt_pk_bf16_f32 v139, v139, v190
	s_and_saveexec_b64 s[58:59], vcc
	v_ashrrev_i32_e32 v190, 7, v189
	v_mul_lo_u32 v190, v190, s29
	v_and_b32_e32 v189, 0x7f, v189
	v_add3_u32 v189, v189, s62, v190
	v_mad_u64_u32 v[190:191], s[60:61], v189, s25, 0
	v_ashrrev_i32_e32 v193, 31, v189
	v_mov_b32_e32 v192, v191
	v_mad_u64_u32 v[192:193], s[60:61], v193, s25, v[192:193]
	v_mov_b32_e32 v191, v192
	v_lshl_add_u64 v[190:191], v[190:191], 1, v[146:147]
	global_store_dwordx4 v[190:191], v[136:139], off nt
.LBB0_43:
	s_or_b64 exec, exec, s[58:59]
	ds_read2_b32 v[136:137], v149 offset0:24 offset1:89
	v_add_u32_e32 v189, s17, v152
	v_cmp_gt_i32_e32 vcc, s24, v189
	s_waitcnt lgkmcnt(0)
	v_mul_f32_e32 v136, v132, v136
	v_mul_f32_e32 v137, v133, v137
	v_cvt_pk_bf16_f32 v136, v136, v137
	ds_read2_b32 v[138:139], v149 offset0:154 offset1:219
	s_waitcnt lgkmcnt(0)
	v_mul_f32_e32 v137, v134, v138
	v_mul_f32_e32 v138, v135, v139
	v_cvt_pk_bf16_f32 v137, v137, v138
	ds_read2_b32 v[138:139], v158 offset0:28 offset1:93
	s_waitcnt lgkmcnt(0)
	v_mul_f32_e32 v138, v128, v138
	v_mul_f32_e32 v139, v129, v139
	v_cvt_pk_bf16_f32 v138, v138, v139
	ds_read2_b32 v[190:191], v158 offset0:158 offset1:223
	s_waitcnt lgkmcnt(0)
	v_mul_f32_e32 v139, v130, v190
	v_mul_f32_e32 v190, v131, v191
	v_cvt_pk_bf16_f32 v139, v139, v190
	s_and_saveexec_b64 s[58:59], vcc
	v_ashrrev_i32_e32 v190, 7, v189
	v_mul_lo_u32 v190, v190, s29
	v_and_b32_e32 v189, 0x7f, v189
	v_add3_u32 v189, v189, s62, v190
	v_mad_u64_u32 v[190:191], s[60:61], v189, s25, 0
	v_ashrrev_i32_e32 v193, 31, v189
	v_mov_b32_e32 v192, v191
	v_mad_u64_u32 v[192:193], s[60:61], v193, s25, v[192:193]
	v_mov_b32_e32 v191, v192
	v_lshl_add_u64 v[190:191], v[190:191], 1, v[146:147]
	global_store_dwordx4 v[190:191], v[136:139], off nt
.LBB0_45:
	s_or_b64 exec, exec, s[58:59]
	ds_read2_b32 v[136:137], v149 offset0:32 offset1:97
	v_add_u32_e32 v189, s17, v153
	v_cmp_gt_i32_e32 vcc, s24, v189
	s_waitcnt lgkmcnt(0)
	v_mul_f32_e32 v136, v132, v136
	v_mul_f32_e32 v137, v133, v137
	v_cvt_pk_bf16_f32 v136, v136, v137
	ds_read2_b32 v[138:139], v149 offset0:162 offset1:227
	s_waitcnt lgkmcnt(0)
	v_mul_f32_e32 v137, v134, v138
	v_mul_f32_e32 v138, v135, v139
	v_cvt_pk_bf16_f32 v137, v137, v138
	ds_read2_b32 v[138:139], v158 offset0:36 offset1:101
	s_waitcnt lgkmcnt(0)
	v_mul_f32_e32 v138, v128, v138
	v_mul_f32_e32 v139, v129, v139
	v_cvt_pk_bf16_f32 v138, v138, v139
	ds_read2_b32 v[190:191], v158 offset0:166 offset1:231
	s_waitcnt lgkmcnt(0)
	v_mul_f32_e32 v139, v130, v190
	v_mul_f32_e32 v190, v131, v191
	v_cvt_pk_bf16_f32 v139, v139, v190
	s_and_saveexec_b64 s[58:59], vcc
	v_ashrrev_i32_e32 v190, 7, v189
	v_mul_lo_u32 v190, v190, s29
	v_and_b32_e32 v189, 0x7f, v189
	v_add3_u32 v189, v189, s62, v190
	v_mad_u64_u32 v[190:191], s[60:61], v189, s25, 0
	v_ashrrev_i32_e32 v193, 31, v189
	v_mov_b32_e32 v192, v191
	v_mad_u64_u32 v[192:193], s[60:61], v193, s25, v[192:193]
	v_mov_b32_e32 v191, v192
	v_lshl_add_u64 v[190:191], v[190:191], 1, v[146:147]
	global_store_dwordx4 v[190:191], v[136:139], off nt
; #define LAS __attribute__((address_space(3)))
; __device__ __forceinline__ unsigned pk2(float lo, float hi) { return pg8::cvt_pk_bf16(lo, hi); }
; __device__ __forceinline__ void p0_finish(bf16* WT, const float* gain, int N, int k0, int n0, int ldw, int blk, int off, int lane, const f32x4 (&v)[16], LAS float* scr) {
;     ...
;     for (int jj = 0; jj < 8; ++jj) { const int n = (lane >> 3) + 8 * jj; const LAS float* s = scr + (8 * c8) * 65 + n;
;         u32x4 o; o.x = pk2(s[0 * 65] * g0[0], s[1 * 65] * g0[1]); o.y = pk2(s[2 * 65] * g0[2], s[3 * 65] * g0[3]); o.z = pk2(s[4 * 65] * g1[0], s[5 * 65] * g1[1]); o.w = pk2(s[6 * 65] * g1[2], s[7 * 65] * g1[3]);
;         const int ng = n0 + n;
;         if (ng < N) { const int row = (ng >> 7) * blk + (ng & 127) + off; __builtin_nontemporal_store(o, (u32x4*)(WT + (size_t)row * ldw + k0 + 8 * c8)); } }
.LBB0_47:
	s_or_b64 exec, exec, s[58:59]
	ds_read2_b32 v[136:137], v149 offset0:40 offset1:105
	v_add_u32_e32 v189, s17, v154
	v_cmp_gt_i32_e32 vcc, s24, v189
	s_waitcnt lgkmcnt(0)
	v_mul_f32_e32 v136, v132, v136
	v_mul_f32_e32 v137, v133, v137
	v_cvt_pk_bf16_f32 v136, v136, v137
	ds_read2_b32 v[138:139], v149 offset0:170 offset1:235
	s_waitcnt lgkmcnt(0)
	v_mul_f32_e32 v137, v134, v138
	v_mul_f32_e32 v138, v135, v139
	v_cvt_pk_bf16_f32 v137, v137, v138
	ds_read2_b32 v[138:139], v158 offset0:44 offset1:109
	s_waitcnt lgkmcnt(0)
	v_mul_f32_e32 v138, v128, v138
	v_mul_f32_e32 v139, v129, v139
	v_cvt_pk_bf16_f32 v138, v138, v139
	ds_read2_b32 v[190:191], v158 offset0:174 offset1:239
	s_waitcnt lgkmcnt(0)
	v_mul_f32_e32 v139, v130, v190
	v_mul_f32_e32 v190, v131, v191
	v_cvt_pk_bf16_f32 v139, v139, v190
	s_and_saveexec_b64 s[58:59], vcc
	v_ashrrev_i32_e32 v190, 7, v189
	v_mul_lo_u32 v190, v190, s29
	v_and_b32_e32 v189, 0x7f, v189
	v_add3_u32 v189, v189, s62, v190
	v_mad_u64_u32 v[190:191], s[60:61], v189, s25, 0
	v_ashrrev_i32_e32 v193, 31, v189
	v_mov_b32_e32 v192, v191
	v_mad_u64_u32 v[192:193], s[60:61], v193, s25, v[192:193]
	v_mov_b32_e32 v191, v192
	v_lshl_add_u64 v[190:191], v[190:191], 1, v[146:147]
	global_store_dwordx4 v[190:191], v[136:139], off nt
.LBB0_49:
	s_or_b64 exec, exec, s[58:59]
	ds_read2_b32 v[136:137], v149 offset0:48 offset1:113
	v_add_u32_e32 v189, s17, v155
	v_cmp_gt_i32_e32 vcc, s24, v189
	s_waitcnt lgkmcnt(0)
	v_mul_f32_e32 v136, v132, v136
	v_mul_f32_e32 v137, v133, v137
	v_cvt_pk_bf16_f32 v136, v136, v137
	ds_read2_b32 v[138:139], v149 offset0:178 offset1:243
	s_waitcnt lgkmcnt(0)
	v_mul_f32_e32 v137, v134, v138
	v_mul_f32_e32 v138, v135, v139
	v_cvt_pk_bf16_f32 v137, v137, v138
	ds_read2_b32 v[138:139], v158 offset0:52 offset1:117
	s_waitcnt lgkmcnt(0)
	v_mul_f32_e32 v138, v128, v138
	v_mul_f32_e32 v139, v129, v139
	v_cvt_pk_bf16_f32 v138, v138, v139
	ds_read2_b32 v[190:191], v158 offset0:182 offset1:247
	s_waitcnt lgkmcnt(0)
	v_mul_f32_e32 v139, v130, v190
	v_mul_f32_e32 v190, v131, v191
	v_cvt_pk_bf16_f32 v139, v139, v190
	s_and_saveexec_b64 s[58:59], vcc
	v_ashrrev_i32_e32 v190, 7, v189
	v_mul_lo_u32 v190, v190, s29
	v_and_b32_e32 v189, 0x7f, v189
	v_add3_u32 v189, v189, s62, v190
	v_mad_u64_u32 v[190:191], s[60:61], v189, s25, 0
	v_ashrrev_i32_e32 v193, 31, v189
	v_mov_b32_e32 v192, v191
	v_mad_u64_u32 v[192:193], s[60:61], v193, s25, v[192:193]
	v_mov_b32_e32 v191, v192
	v_lshl_add_u64 v[190:191], v[190:191], 1, v[146:147]
	global_store_dwordx4 v[190:191], v[136:139], off nt
.LBB0_51:
	s_or_b64 exec, exec, s[58:59]
	ds_read2_b32 v[136:137], v149 offset0:56 offset1:121
	s_waitcnt lgkmcnt(0)
	v_mul_f32_e32 v132, v132, v136
	v_mul_f32_e32 v133, v133, v137
	v_cvt_pk_bf16_f32 v132, v132, v133
	ds_read2_b32 v[136:137], v149 offset0:186 offset1:251
	s_waitcnt lgkmcnt(0)
	v_mul_f32_e32 v133, v134, v136
	v_mul_f32_e32 v134, v135, v137
	v_cvt_pk_bf16_f32 v133, v133, v134
	ds_read2_b32 v[134:135], v158 offset0:60 offset1:125
	s_waitcnt lgkmcnt(0)
	v_mul_f32_e32 v128, v128, v134
	v_mul_f32_e32 v129, v129, v135
	v_cvt_pk_bf16_f32 v134, v128, v129
	ds_read2_b32 v[136:137], v158 offset0:190 offset1:255
	v_add_u32_e32 v128, s17, v157
	v_cmp_gt_i32_e32 vcc, s24, v128
	s_waitcnt lgkmcnt(0)
	v_mul_f32_e32 v129, v130, v136
	v_mul_f32_e32 v130, v131, v137
	v_cvt_pk_bf16_f32 v135, v129, v130
	s_and_saveexec_b64 s[58:59], vcc
	v_ashrrev_i32_e32 v129, 7, v128
	v_mul_lo_u32 v129, v129, s29
	v_and_b32_e32 v128, 0x7f, v128
	v_add3_u32 v128, v128, s62, v129
	v_ashrrev_i32_e32 v131, 31, v128
	v_mad_u64_u32 v[128:129], s[60:61], v128, s25, 0
	v_mov_b32_e32 v130, v129
	v_mad_u64_u32 v[130:131], s[60:61], v131, s25, v[130:131]
	v_mov_b32_e32 v129, v130
	v_lshl_add_u64 v[128:129], v[128:129], 1, v[146:147]
	global_store_dwordx4 v[128:129], v[132:135], off nt

; __device__ __forceinline__ void p0_load(const float* W, int N, int k0, int n0, int lane, f32x4 (&v)[16]) {
;     const int c = lane & 15, rq = lane >> 4;
;     int col = n0 + 4 * c; col = col < N - 4 ? col : N - 4;
;     const float* p = W + (size_t)(k0 + rq) * N + col;
; #pragma unroll
;     for (int j = 0; j < 16; ++j) v[j] = __builtin_nontemporal_load((const f32x4*)(p + (size_t)(4 * j) * N));
; }
.LBB0_64:
	s_load_dwordx2 s[58:59], s[58:59], 0x0
	v_add_u32_e32 v1, s30, v141
	v_mad_u64_u32 v[2:3], s[60:61], v1, s24, 0
	v_ashrrev_i32_e32 v5, 31, v1
	v_mov_b32_e32 v4, v3
	v_add_u32_e32 v0, s17, v143
	s_add_i32 s21, s24, -4
	v_mad_u64_u32 v[4:5], s[60:61], v5, s24, v[4:5]
	v_min_i32_e32 v0, s21, v0
	v_mov_b32_e32 v3, v4
	s_waitcnt lgkmcnt(0)
	v_lshl_add_u64 v[2:3], v[2:3], 2, s[58:59]
	v_ashrrev_i32_e32 v1, 31, v0
	v_lshl_add_u64 v[12:13], v[0:1], 2, v[2:3]
	s_lshl_b32 s38, s24, 2
	v_lshl_add_u64 v[0:1], s[38:39], 2, v[12:13]
	s_lshl_b32 s38, s24, 3
	global_load_dwordx4 v[28:31], v[12:13], off nt
	global_load_dwordx4 v[24:27], v[0:1], off nt
	v_lshl_add_u64 v[0:1], s[38:39], 2, v[12:13]
	s_mul_i32 s38, s24, 12
	v_lshl_add_u64 v[2:3], s[38:39], 2, v[12:13]
	s_lshl_b32 s38, s24, 4
	global_load_dwordx4 v[36:39], v[0:1], off nt
	global_load_dwordx4 v[32:35], v[2:3], off nt
	v_lshl_add_u64 v[0:1], s[38:39], 2, v[12:13]
	s_mul_i32 s38, s24, 20
	v_lshl_add_u64 v[2:3], s[38:39], 2, v[12:13]
	s_mul_i32 s38, s24, 24
	global_load_dwordx4 v[44:47], v[0:1], off nt
	global_load_dwordx4 v[40:43], v[2:3], off nt
	v_lshl_add_u64 v[0:1], s[38:39], 2, v[12:13]
	s_mul_i32 s38, s24, 28
	v_lshl_add_u64 v[2:3], s[38:39], 2, v[12:13]
	s_lshl_b32 s38, s24, 5
	global_load_dwordx4 v[52:55], v[0:1], off nt
	global_load_dwordx4 v[48:51], v[2:3], off nt
	v_lshl_add_u64 v[0:1], s[38:39], 2, v[12:13]
	s_mul_i32 s38, s24, 36
	v_lshl_add_u64 v[2:3], s[38:39], 2, v[12:13]
	s_mul_i32 s38, s24, 40
	global_load_dwordx4 v[56:59], v[0:1], off nt
	global_load_dwordx4 v[8:11], v[2:3], off nt
	v_lshl_add_u64 v[0:1], s[38:39], 2, v[12:13]
	s_mul_i32 s38, s24, 44
	v_lshl_add_u64 v[2:3], s[38:39], 2, v[12:13]
	s_mul_i32 s38, s24, 48
	global_load_dwordx4 v[20:23], v[0:1], off nt
	global_load_dwordx4 v[4:7], v[2:3], off nt
	v_lshl_add_u64 v[0:1], s[38:39], 2, v[12:13]
	s_mul_i32 s38, s24, 52
	v_lshl_add_u64 v[2:3], s[38:39], 2, v[12:13]
	s_mul_i32 s38, s24, 56
	v_lshl_add_u64 v[14:15], s[38:39], 2, v[12:13]
	s_mul_i32 s38, s24, 60
	v_lshl_add_u64 v[68:69], s[38:39], 2, v[12:13]
	global_load_dwordx4 v[16:19], v[0:1], off nt
	s_nop 0
	global_load_dwordx4 v[0:3], v[2:3], off nt
	s_nop 0
	global_load_dwordx4 v[12:15], v[14:15], off nt
	s_nop 0
	global_load_dwordx4 v[68:71], v[68:69], off nt
.LBB0_65:
	s_ashr_i32 s31, s30, 31
	s_cmp_eq_u64 s[4:5], 0
	s_cbranch_scc1 .LBB0_67
	s_lshl_b64 s[58:59], s[30:31], 2
	s_add_u32 s58, s4, s58
	s_addc_u32 s59, s5, s59
	v_lshlrev_b32_e32 v132, 2, v142
	global_load_dwordx4 v[128:131], v132, s[58:59] offset:16
	s_nop 0
	global_load_dwordx4 v[132:135], v132, s[58:59]
	s_branch .LBB0_68

.LBB0_68:
	s_ashr_i32 s53, s52, 31
	s_cmp_lg_u64 s[56:57], 0
	s_cbranch_scc1 .Lp0w_b0
	s_waitcnt vmcnt(26)
	s_branch .Lp0w_b1

; #define LAS __attribute__((address_space(3)))
; __device__ __forceinline__ unsigned pk2(float lo, float hi) { return pg8::cvt_pk_bf16(lo, hi); }
; __device__ __forceinline__ void p0_finish(bf16* WT, const float* gain, int N, int k0, int n0, int ldw, int blk, int off, int lane, const f32x4 (&v)[16], LAS float* scr) {
;     const int c = lane & 15, rq = lane >> 4, c8 = lane & 7;
;     f32x4 g0 = {1.f, 1.f, 1.f, 1.f}, g1 = g0;
;     if (gain) { g0 = *(const f32x4*)(gain + k0 + 8 * c8); g1 = *(const f32x4*)(gain + k0 + 8 * c8 + 4); }
; #pragma unroll
;     for (int j = 0; j < 16; ++j) { LAS float* s = scr + (4 * j + rq) * 65 + 4 * c; s[0] = v[j][0]; s[1] = v[j][1]; s[2] = v[j][2]; s[3] = v[j][3]; }
;     asm volatile("s_waitcnt lgkmcnt(0)" ::: "memory");
; #pragma unroll
;     for (int jj = 0; jj < 8; ++jj) { const int n = (lane >> 3) + 8 * jj; const LAS float* s = scr + (8 * c8) * 65 + n;
;         u32x4 o; o.x = pk2(s[0 * 65] * g0[0], s[1 * 65] * g0[1]); o.y = pk2(s[2 * 65] * g0[2], s[3 * 65] * g0[3]); o.z = pk2(s[4 * 65] * g1[0], s[5 * 65] * g1[1]); o.w = pk2(s[6 * 65] * g1[2], s[7 * 65] * g1[3]);
;         const int ng = n0 + n;
;         if (ng < N) { const int row = (ng >> 7) * blk + (ng & 127) + off; __builtin_nontemporal_store(o, (u32x4*)(WT + (size_t)row * ldw + k0 + 8 * c8)); } }
.Lp0w_b1:
	ds_write2_b32 v156, v64, v65 offset1:1
	ds_write2_b32 v156, v66, v67 offset0:2 offset1:3
	ds_write2_b32 v159, v60, v61 offset1:1
	ds_write2_b32 v160, v62, v63 offset1:1
	ds_write2_b32 v161, v76, v77 offset1:1
	ds_write2_b32 v162, v78, v79 offset1:1
	ds_write2_b32 v163, v72, v73 offset1:1
	ds_write2_b32 v164, v74, v75 offset1:1
	ds_write2_b32 v165, v84, v85 offset1:1
	ds_write2_b32 v166, v86, v87 offset1:1
	ds_write2_b32 v167, v80, v81 offset1:1
	ds_write2_b32 v168, v82, v83 offset1:1
	ds_write2_b32 v169, v92, v93 offset1:1
	ds_write2_b32 v170, v94, v95 offset1:1
	ds_write2_b32 v171, v88, v89 offset1:1
	ds_write2_b32 v172, v90, v91 offset1:1
	ds_write2_b32 v173, v100, v101 offset1:1
	ds_write2_b32 v174, v102, v103 offset1:1
	ds_write2_b32 v175, v96, v97 offset1:1
	ds_write2_b32 v176, v98, v99 offset1:1
	ds_write2_b32 v177, v108, v109 offset1:1
	ds_write2_b32 v178, v110, v111 offset1:1
	ds_write2_b32 v179, v104, v105 offset1:1
	ds_write2_b32 v180, v106, v107 offset1:1
	ds_write2_b32 v181, v116, v117 offset1:1
	ds_write2_b32 v182, v118, v119 offset1:1
	ds_write2_b32 v183, v112, v113 offset1:1
	ds_write2_b32 v184, v114, v115 offset1:1
	ds_write2_b32 v185, v124, v125 offset1:1
	ds_write2_b32 v186, v126, v127 offset1:1
	ds_write2_b32 v187, v120, v121 offset1:1
	ds_write2_b32 v188, v122, v123 offset1:1
	s_waitcnt lgkmcnt(0)
	ds_read2_b32 v[136:137], v149 offset1:65
	s_lshl_b64 s[58:59], s[52:53], 1
	s_add_u32 s58, s54, s58
	s_addc_u32 s59, s55, s59
	v_lshl_add_u64 v[146:147], s[58:59], 0, v[144:145]
	s_waitcnt lgkmcnt(0)
	v_mul_f32_e32 v136, v232, v136
	v_mul_f32_e32 v137, v233, v137
	v_cvt_pk_bf16_f32 v136, v136, v137
	ds_read2_b32 v[138:139], v149 offset0:130 offset1:195
	s_waitcnt lgkmcnt(0)
	v_mul_f32_e32 v137, v234, v138
	v_mul_f32_e32 v138, v235, v139
	v_cvt_pk_bf16_f32 v137, v137, v138
	ds_read2_b32 v[138:139], v158 offset0:4 offset1:69
	s_waitcnt lgkmcnt(0)
	v_mul_f32_e32 v138, v228, v138
	v_mul_f32_e32 v139, v229, v139
	v_cvt_pk_bf16_f32 v138, v138, v139
	ds_read2_b32 v[160:161], v158 offset0:134 offset1:199
	s_waitcnt lgkmcnt(0)
	v_mul_f32_e32 v139, v230, v160
	v_mul_f32_e32 v159, v231, v161
	v_cvt_pk_bf16_f32 v139, v139, v159
	v_add_u32_e32 v159, s68, v148
	v_cmp_gt_i32_e32 vcc, s69, v159
	s_and_saveexec_b64 s[58:59], vcc
	v_ashrrev_i32_e32 v160, 7, v159
	v_mul_lo_u32 v160, v160, s20
	v_and_b32_e32 v159, 0x7f, v159
	v_add3_u32 v159, v159, s71, v160
	v_mad_u64_u32 v[160:161], s[60:61], v159, s70, 0
	v_ashrrev_i32_e32 v163, 31, v159
	v_mov_b32_e32 v162, v161
	v_mad_u64_u32 v[162:163], s[60:61], v163, s70, v[162:163]
	v_mov_b32_e32 v161, v162
	v_lshl_add_u64 v[160:161], v[160:161], 1, v[146:147]
	global_store_dwordx4 v[160:161], v[136:139], off nt
.LBB0_70:
	s_or_b64 exec, exec, s[58:59]
	ds_read2_b32 v[136:137], v149 offset0:8 offset1:73
	v_add_u32_e32 v159, s68, v150
	v_cmp_gt_i32_e32 vcc, s69, v159
	s_waitcnt lgkmcnt(0)
	v_mul_f32_e32 v136, v232, v136
	v_mul_f32_e32 v137, v233, v137
	v_cvt_pk_bf16_f32 v136, v136, v137
	ds_read2_b32 v[138:139], v149 offset0:138 offset1:203
	s_waitcnt lgkmcnt(0)
	v_mul_f32_e32 v137, v234, v138
	v_mul_f32_e32 v138, v235, v139
	v_cvt_pk_bf16_f32 v137, v137, v138
	ds_read2_b32 v[138:139], v158 offset0:12 offset1:77
	s_waitcnt lgkmcnt(0)
	v_mul_f32_e32 v138, v228, v138
	v_mul_f32_e32 v139, v229, v139
	v_cvt_pk_bf16_f32 v138, v138, v139
	ds_read2_b32 v[160:161], v158 offset0:142 offset1:207
	s_waitcnt lgkmcnt(0)
	v_mul_f32_e32 v139, v230, v160
	v_mul_f32_e32 v160, v231, v161
	v_cvt_pk_bf16_f32 v139, v139, v160
	s_and_saveexec_b64 s[58:59], vcc
	v_ashrrev_i32_e32 v160, 7, v159
	v_mul_lo_u32 v160, v160, s20
	v_and_b32_e32 v159, 0x7f, v159
	v_add3_u32 v159, v159, s71, v160
	v_mad_u64_u32 v[160:161], s[60:61], v159, s70, 0
	v_ashrrev_i32_e32 v163, 31, v159
	v_mov_b32_e32 v162, v161
	v_mad_u64_u32 v[162:163], s[60:61], v163, s70, v[162:163]
	v_mov_b32_e32 v161, v162
	v_lshl_add_u64 v[160:161], v[160:161], 1, v[146:147]
	global_store_dwordx4 v[160:161], v[136:139], off nt
.LBB0_72:
	s_or_b64 exec, exec, s[58:59]
	ds_read2_b32 v[136:137], v149 offset0:16 offset1:81
	v_add_u32_e32 v159, s68, v151
	v_cmp_gt_i32_e32 vcc, s69, v159
	s_waitcnt lgkmcnt(0)
	v_mul_f32_e32 v136, v232, v136
	v_mul_f32_e32 v137, v233, v137
	v_cvt_pk_bf16_f32 v136, v136, v137
	ds_read2_b32 v[138:139], v149 offset0:146 offset1:211
	s_waitcnt lgkmcnt(0)
	v_mul_f32_e32 v137, v234, v138
	v_mul_f32_e32 v138, v235, v139
	v_cvt_pk_bf16_f32 v137, v137, v138
	ds_read2_b32 v[138:139], v158 offset0:20 offset1:85
	s_waitcnt lgkmcnt(0)
	v_mul_f32_e32 v138, v228, v138
	v_mul_f32_e32 v139, v229, v139
	v_cvt_pk_bf16_f32 v138, v138, v139
	ds_read2_b32 v[160:161], v158 offset0:150 offset1:215
	s_waitcnt lgkmcnt(0)
	v_mul_f32_e32 v139, v230, v160
	v_mul_f32_e32 v160, v231, v161
	v_cvt_pk_bf16_f32 v139, v139, v160
	s_and_saveexec_b64 s[58:59], vcc
	v_ashrrev_i32_e32 v160, 7, v159
	v_mul_lo_u32 v160, v160, s20
	v_and_b32_e32 v159, 0x7f, v159
	v_add3_u32 v159, v159, s71, v160
	v_mad_u64_u32 v[160:161], s[60:61], v159, s70, 0
	v_ashrrev_i32_e32 v163, 31, v159
	v_mov_b32_e32 v162, v161
	v_mad_u64_u32 v[162:163], s[60:61], v163, s70, v[162:163]
	v_mov_b32_e32 v161, v162
	v_lshl_add_u64 v[160:161], v[160:161], 1, v[146:147]
	global_store_dwordx4 v[160:161], v[136:139], off nt
; #define LAS __attribute__((address_space(3)))
; __device__ __forceinline__ unsigned pk2(float lo, float hi) { return pg8::cvt_pk_bf16(lo, hi); }
; __device__ __forceinline__ void p0_finish(bf16* WT, const float* gain, int N, int k0, int n0, int ldw, int blk, int off, int lane, const f32x4 (&v)[16], LAS float* scr) {
;     ...
;     for (int jj = 0; jj < 8; ++jj) { const int n = (lane >> 3) + 8 * jj; const LAS float* s = scr + (8 * c8) * 65 + n;
;         u32x4 o; o.x = pk2(s[0 * 65] * g0[0], s[1 * 65] * g0[1]); o.y = pk2(s[2 * 65] * g0[2], s[3 * 65] * g0[3]); o.z = pk2(s[4 * 65] * g1[0], s[5 * 65] * g1[1]); o.w = pk2(s[6 * 65] * g1[2], s[7 * 65] * g1[3]);
;         const int ng = n0 + n;
;         if (ng < N) { const int row = (ng >> 7) * blk + (ng & 127) + off; __builtin_nontemporal_store(o, (u32x4*)(WT + (size_t)row * ldw + k0 + 8 * c8)); } }
.LBB0_74:
	s_or_b64 exec, exec, s[58:59]
	ds_read2_b32 v[136:137], v149 offset0:24 offset1:89
	v_add_u32_e32 v159, s68, v152
	v_cmp_gt_i32_e32 vcc, s69, v159
	s_waitcnt lgkmcnt(0)
	v_mul_f32_e32 v136, v232, v136
	v_mul_f32_e32 v137, v233, v137
	v_cvt_pk_bf16_f32 v136, v136, v137
	ds_read2_b32 v[138:139], v149 offset0:154 offset1:219
	s_waitcnt lgkmcnt(0)
	v_mul_f32_e32 v137, v234, v138
	v_mul_f32_e32 v138, v235, v139
	v_cvt_pk_bf16_f32 v137, v137, v138
	ds_read2_b32 v[138:139], v158 offset0:28 offset1:93
	s_waitcnt lgkmcnt(0)
	v_mul_f32_e32 v138, v228, v138
	v_mul_f32_e32 v139, v229, v139
	v_cvt_pk_bf16_f32 v138, v138, v139
	ds_read2_b32 v[160:161], v158 offset0:158 offset1:223
	s_waitcnt lgkmcnt(0)
	v_mul_f32_e32 v139, v230, v160
	v_mul_f32_e32 v160, v231, v161
	v_cvt_pk_bf16_f32 v139, v139, v160
	s_and_saveexec_b64 s[58:59], vcc
	v_ashrrev_i32_e32 v160, 7, v159
	v_mul_lo_u32 v160, v160, s20
	v_and_b32_e32 v159, 0x7f, v159
	v_add3_u32 v159, v159, s71, v160
	v_mad_u64_u32 v[160:161], s[60:61], v159, s70, 0
	v_ashrrev_i32_e32 v163, 31, v159
	v_mov_b32_e32 v162, v161
	v_mad_u64_u32 v[162:163], s[60:61], v163, s70, v[162:163]
	v_mov_b32_e32 v161, v162
	v_lshl_add_u64 v[160:161], v[160:161], 1, v[146:147]
	global_store_dwordx4 v[160:161], v[136:139], off nt
.LBB0_76:
	s_or_b64 exec, exec, s[58:59]
	ds_read2_b32 v[136:137], v149 offset0:32 offset1:97
	v_add_u32_e32 v159, s68, v153
	v_cmp_gt_i32_e32 vcc, s69, v159
	s_waitcnt lgkmcnt(0)
	v_mul_f32_e32 v136, v232, v136
	v_mul_f32_e32 v137, v233, v137
	v_cvt_pk_bf16_f32 v136, v136, v137
	ds_read2_b32 v[138:139], v149 offset0:162 offset1:227
	s_waitcnt lgkmcnt(0)
	v_mul_f32_e32 v137, v234, v138
	v_mul_f32_e32 v138, v235, v139
	v_cvt_pk_bf16_f32 v137, v137, v138
	ds_read2_b32 v[138:139], v158 offset0:36 offset1:101
	s_waitcnt lgkmcnt(0)
	v_mul_f32_e32 v138, v228, v138
	v_mul_f32_e32 v139, v229, v139
	v_cvt_pk_bf16_f32 v138, v138, v139
	ds_read2_b32 v[160:161], v158 offset0:166 offset1:231
	s_waitcnt lgkmcnt(0)
	v_mul_f32_e32 v139, v230, v160
	v_mul_f32_e32 v160, v231, v161
	v_cvt_pk_bf16_f32 v139, v139, v160
	s_and_saveexec_b64 s[58:59], vcc
	v_ashrrev_i32_e32 v160, 7, v159
	v_mul_lo_u32 v160, v160, s20
	v_and_b32_e32 v159, 0x7f, v159
	v_add3_u32 v159, v159, s71, v160
	v_mad_u64_u32 v[160:161], s[60:61], v159, s70, 0
	v_ashrrev_i32_e32 v163, 31, v159
	v_mov_b32_e32 v162, v161
	v_mad_u64_u32 v[162:163], s[60:61], v163, s70, v[162:163]
	v_mov_b32_e32 v161, v162
	v_lshl_add_u64 v[160:161], v[160:161], 1, v[146:147]
	global_store_dwordx4 v[160:161], v[136:139], off nt
.LBB0_78:
	s_or_b64 exec, exec, s[58:59]
	ds_read2_b32 v[136:137], v149 offset0:40 offset1:105
	v_add_u32_e32 v159, s68, v154
	v_cmp_gt_i32_e32 vcc, s69, v159
	s_waitcnt lgkmcnt(0)
	v_mul_f32_e32 v136, v232, v136
	v_mul_f32_e32 v137, v233, v137
	v_cvt_pk_bf16_f32 v136, v136, v137
	ds_read2_b32 v[138:139], v149 offset0:170 offset1:235
	s_waitcnt lgkmcnt(0)
	v_mul_f32_e32 v137, v234, v138
	v_mul_f32_e32 v138, v235, v139
	v_cvt_pk_bf16_f32 v137, v137, v138
	ds_read2_b32 v[138:139], v158 offset0:44 offset1:109
	s_waitcnt lgkmcnt(0)
	v_mul_f32_e32 v138, v228, v138
	v_mul_f32_e32 v139, v229, v139
	v_cvt_pk_bf16_f32 v138, v138, v139
	ds_read2_b32 v[160:161], v158 offset0:174 offset1:239
	s_waitcnt lgkmcnt(0)
	v_mul_f32_e32 v139, v230, v160
	v_mul_f32_e32 v160, v231, v161
	v_cvt_pk_bf16_f32 v139, v139, v160
	s_and_saveexec_b64 s[58:59], vcc
	v_ashrrev_i32_e32 v160, 7, v159
	v_mul_lo_u32 v160, v160, s20
	v_and_b32_e32 v159, 0x7f, v159
	v_add3_u32 v159, v159, s71, v160
	v_mad_u64_u32 v[160:161], s[60:61], v159, s70, 0
	v_ashrrev_i32_e32 v163, 31, v159
	v_mov_b32_e32 v162, v161
	v_mad_u64_u32 v[162:163], s[60:61], v163, s70, v[162:163]
	v_mov_b32_e32 v161, v162
	v_lshl_add_u64 v[160:161], v[160:161], 1, v[146:147]
	global_store_dwordx4 v[160:161], v[136:139], off nt
.LBB0_80:
	s_or_b64 exec, exec, s[58:59]
	ds_read2_b32 v[136:137], v149 offset0:48 offset1:113
	v_add_u32_e32 v159, s68, v155
	v_cmp_gt_i32_e32 vcc, s69, v159
	s_waitcnt lgkmcnt(0)
	v_mul_f32_e32 v136, v232, v136
	v_mul_f32_e32 v137, v233, v137
	v_cvt_pk_bf16_f32 v136, v136, v137
	ds_read2_b32 v[138:139], v149 offset0:178 offset1:243
	s_waitcnt lgkmcnt(0)
	v_mul_f32_e32 v137, v234, v138
	v_mul_f32_e32 v138, v235, v139
	v_cvt_pk_bf16_f32 v137, v137, v138
	ds_read2_b32 v[138:139], v158 offset0:52 offset1:117
	s_waitcnt lgkmcnt(0)
	v_mul_f32_e32 v138, v228, v138
	v_mul_f32_e32 v139, v229, v139
	v_cvt_pk_bf16_f32 v138, v138, v139
	ds_read2_b32 v[160:161], v158 offset0:182 offset1:247
	s_waitcnt lgkmcnt(0)
	v_mul_f32_e32 v139, v230, v160
	v_mul_f32_e32 v160, v231, v161
	v_cvt_pk_bf16_f32 v139, v139, v160
	s_and_saveexec_b64 s[58:59], vcc
	v_ashrrev_i32_e32 v160, 7, v159
	v_mul_lo_u32 v160, v160, s20
	v_and_b32_e32 v159, 0x7f, v159
	v_add3_u32 v159, v159, s71, v160
	v_mad_u64_u32 v[160:161], s[60:61], v159, s70, 0
	v_ashrrev_i32_e32 v163, 31, v159
	v_mov_b32_e32 v162, v161
	v_mad_u64_u32 v[162:163], s[60:61], v163, s70, v[162:163]
	v_mov_b32_e32 v161, v162
	v_lshl_add_u64 v[160:161], v[160:161], 1, v[146:147]
	global_store_dwordx4 v[160:161], v[136:139], off nt
.LBB0_82:
	s_or_b64 exec, exec, s[58:59]
	ds_read2_b32 v[136:137], v149 offset0:56 offset1:121
	s_waitcnt lgkmcnt(0)
	v_mul_f32_e32 v232, v232, v136
	v_mul_f32_e32 v233, v233, v137
	v_cvt_pk_bf16_f32 v232, v232, v233
	ds_read2_b32 v[136:137], v149 offset0:186 offset1:251
	s_waitcnt lgkmcnt(0)
	v_mul_f32_e32 v233, v234, v136
	v_mul_f32_e32 v234, v235, v137
	v_cvt_pk_bf16_f32 v233, v233, v234
	ds_read2_b32 v[234:235], v158 offset0:60 offset1:125
	s_waitcnt lgkmcnt(0)
	v_mul_f32_e32 v228, v228, v234
	v_mul_f32_e32 v229, v229, v235
	v_cvt_pk_bf16_f32 v234, v228, v229
	ds_read2_b32 v[136:137], v158 offset0:190 offset1:255
	v_add_u32_e32 v228, s68, v157
	v_cmp_gt_i32_e32 vcc, s69, v228
	s_waitcnt lgkmcnt(0)
	v_mul_f32_e32 v229, v230, v136
	v_mul_f32_e32 v230, v231, v137
	v_cvt_pk_bf16_f32 v235, v229, v230
	s_and_saveexec_b64 s[58:59], vcc
	v_ashrrev_i32_e32 v229, 7, v228
	v_mul_lo_u32 v229, v229, s20
	v_and_b32_e32 v228, 0x7f, v228
	v_add3_u32 v228, v228, s71, v229
	v_ashrrev_i32_e32 v231, 31, v228
	v_mad_u64_u32 v[228:229], s[60:61], v228, s70, 0
	v_mov_b32_e32 v230, v229
	v_mad_u64_u32 v[230:231], s[60:61], v231, s70, v[230:231]
	v_mov_b32_e32 v229, v230
	v_lshl_add_u64 v[228:229], v[228:229], 1, v[146:147]
	global_store_dwordx4 v[228:229], v[232:235], off nt
	s_branch .LBB0_21
